# setup de-serialisation: MoBA Q rows loaded early (4 in flight, stored before the barrier), item table by 32-lane prefix scan, SWA bias table loads unrolled (5 in flight)
# speedup vs baseline: 1.0117x; 1.0117x over previous
; __device__ __forceinline__ void swa_unit(lbyte* lds, const bf16* QKV, bf16* AO, const float* rel_bias, const float* sinks, int b, int hkv, int qb) {
;     ...
; #pragma unroll
;     for (int i = tid; i < 8 * 320; i += NT) { const int w = i / 320, dist = i % 320 - 64; bt[i] = (dist >= 0 && dist < 128) ? rel_bias[t5_bucket(dist > 0 ? dist : 0) * 16 + 8 * hkv + w] * LOG2E : -INFINITY; }
.LBB0_532:
	s_or_b64 exec, exec, s[8:9]
	s_lshl_b32 s26, s26, 3
	v_cmp_gt_i32_e32 vcc, s72, v11
	s_and_saveexec_b64 s[8:9], vcc
	s_cbranch_execz .LBB0_537
	v_lshl_add_u32 v0, v11, 2, s28
	v_mov_b32_e32 v2, v11
	v_mov_b32_e32 v8, 0xff800000
	s_mov_b32 s16, 0x66666667
	v_mul_hi_i32 v3, v2, s16
	v_lshrrev_b32_e32 v4, 31, v3
	v_ashrrev_i32_e32 v3, 7, v3
	v_add_u32_e32 v3, v3, v4
	v_mul_i32_i24_e32 v4, 0x140, v3
	v_sub_u32_e32 v4, v2, v4
	v_subrev_u32_e32 v4, 64, v4
	s_movk_i32 s16, 0x80
	v_cmp_gt_u32_e32 vcc, s16, v4
	s_mov_b64 s[30:31], vcc
	s_and_saveexec_b64 s[16:17], vcc
	s_cbranch_execz .Lswab_skip0
	v_max_u32_e32 v5, 16, v4
	v_ffbh_u32_e32 v6, v5
	v_lshlrev_b32_e32 v6, 1, v6
	v_sub_u32_e32 v7, 62, v6
	v_mul_lo_u32 v5, v5, v5
	v_lshlrev_b32_e64 v7, v7, 2
	v_cmp_ge_u32_e32 vcc, v5, v7
	s_nop 1
	v_cndmask_b32_e64 v5, 0, 1, vcc
	v_sub_u32_e32 v5, v5, v6
	v_add_u32_e32 v5, 0x46, v5
	v_cmp_gt_u32_e32 vcc, 16, v4
	s_nop 1
	v_cndmask_b32_e32 v4, v5, v4, vcc
	v_lshlrev_b32_e32 v4, 4, v4
	v_add3_u32 v4, v3, s26, v4
	v_ashrrev_i32_e32 v5, 31, v4
	v_lshl_add_u64 v[4:5], v[4:5], 2, s[6:7]
	global_load_dword v12, v[4:5], off
.Lswab_skip0:
	s_or_b64 exec, exec, s[16:17]
	v_add_u32_e32 v2, 0x200, v2
	s_mov_b32 s16, 0x66666667
	v_mul_hi_i32 v3, v2, s16
	v_lshrrev_b32_e32 v4, 31, v3
	v_ashrrev_i32_e32 v3, 7, v3
	v_add_u32_e32 v3, v3, v4
	v_mul_i32_i24_e32 v4, 0x140, v3
	v_sub_u32_e32 v4, v2, v4
	v_subrev_u32_e32 v4, 64, v4
	s_movk_i32 s16, 0x80
	v_cmp_gt_u32_e32 vcc, s16, v4
	s_mov_b64 s[40:41], vcc
	s_and_saveexec_b64 s[16:17], vcc
	s_cbranch_execz .Lswab_skip1
	v_max_u32_e32 v5, 16, v4
	v_ffbh_u32_e32 v6, v5
	v_lshlrev_b32_e32 v6, 1, v6
	v_sub_u32_e32 v7, 62, v6
	v_mul_lo_u32 v5, v5, v5
	v_lshlrev_b32_e64 v7, v7, 2
	v_cmp_ge_u32_e32 vcc, v5, v7
	s_nop 1
	v_cndmask_b32_e64 v5, 0, 1, vcc
	v_sub_u32_e32 v5, v5, v6
	v_add_u32_e32 v5, 0x46, v5
	v_cmp_gt_u32_e32 vcc, 16, v4
	s_nop 1
	v_cndmask_b32_e32 v4, v5, v4, vcc
	v_lshlrev_b32_e32 v4, 4, v4
	v_add3_u32 v4, v3, s26, v4
	v_ashrrev_i32_e32 v5, 31, v4
	v_lshl_add_u64 v[4:5], v[4:5], 2, s[6:7]
	global_load_dword v13, v[4:5], off
.Lswab_skip1:
	s_or_b64 exec, exec, s[16:17]
	v_add_u32_e32 v2, 0x200, v2
	s_mov_b32 s16, 0x66666667
	v_mul_hi_i32 v3, v2, s16
	v_lshrrev_b32_e32 v4, 31, v3
	v_ashrrev_i32_e32 v3, 7, v3
	v_add_u32_e32 v3, v3, v4
	v_mul_i32_i24_e32 v4, 0x140, v3
	v_sub_u32_e32 v4, v2, v4
	v_subrev_u32_e32 v4, 64, v4
	s_movk_i32 s16, 0x80
	v_cmp_gt_u32_e32 vcc, s16, v4
	s_mov_b64 s[44:45], vcc
	s_and_saveexec_b64 s[16:17], vcc
	s_cbranch_execz .Lswab_skip2
	v_max_u32_e32 v5, 16, v4
	v_ffbh_u32_e32 v6, v5
	v_lshlrev_b32_e32 v6, 1, v6
	v_sub_u32_e32 v7, 62, v6
	v_mul_lo_u32 v5, v5, v5
	v_lshlrev_b32_e64 v7, v7, 2
	v_cmp_ge_u32_e32 vcc, v5, v7
	s_nop 1
	v_cndmask_b32_e64 v5, 0, 1, vcc
	v_sub_u32_e32 v5, v5, v6
	v_add_u32_e32 v5, 0x46, v5
	v_cmp_gt_u32_e32 vcc, 16, v4
	s_nop 1
	v_cndmask_b32_e32 v4, v5, v4, vcc
	v_lshlrev_b32_e32 v4, 4, v4
	v_add3_u32 v4, v3, s26, v4
	v_ashrrev_i32_e32 v5, 31, v4
	v_lshl_add_u64 v[4:5], v[4:5], 2, s[6:7]
	global_load_dword v14, v[4:5], off
.Lswab_skip2:
	s_or_b64 exec, exec, s[16:17]
	v_add_u32_e32 v2, 0x200, v2
	s_mov_b32 s16, 0x66666667
	v_mul_hi_i32 v3, v2, s16
	v_lshrrev_b32_e32 v4, 31, v3
	v_ashrrev_i32_e32 v3, 7, v3
	v_add_u32_e32 v3, v3, v4
	v_mul_i32_i24_e32 v4, 0x140, v3
	v_sub_u32_e32 v4, v2, v4
	v_subrev_u32_e32 v4, 64, v4
	s_movk_i32 s16, 0x80
	v_cmp_gt_u32_e32 vcc, s16, v4
	s_mov_b64 s[48:49], vcc
	s_and_saveexec_b64 s[16:17], vcc
	s_cbranch_execz .Lswab_skip3
	v_max_u32_e32 v5, 16, v4
	v_ffbh_u32_e32 v6, v5
	v_lshlrev_b32_e32 v6, 1, v6
	v_sub_u32_e32 v7, 62, v6
	v_mul_lo_u32 v5, v5, v5
	v_lshlrev_b32_e64 v7, v7, 2
	v_cmp_ge_u32_e32 vcc, v5, v7
	s_nop 1
	v_cndmask_b32_e64 v5, 0, 1, vcc
	v_sub_u32_e32 v5, v5, v6
	v_add_u32_e32 v5, 0x46, v5
	v_cmp_gt_u32_e32 vcc, 16, v4
	s_nop 1
	v_cndmask_b32_e32 v4, v5, v4, vcc
	v_lshlrev_b32_e32 v4, 4, v4
	v_add3_u32 v4, v3, s26, v4
	v_ashrrev_i32_e32 v5, 31, v4
	v_lshl_add_u64 v[4:5], v[4:5], 2, s[6:7]
	global_load_dword v15, v[4:5], off
.Lswab_skip3:
	s_or_b64 exec, exec, s[16:17]
	v_add_u32_e32 v2, 0x200, v2
	s_mov_b32 s16, 0x66666667
	v_mul_hi_i32 v3, v2, s16
	v_lshrrev_b32_e32 v4, 31, v3
	v_ashrrev_i32_e32 v3, 7, v3
	v_add_u32_e32 v3, v3, v4
	v_mul_i32_i24_e32 v4, 0x140, v3
	v_sub_u32_e32 v4, v2, v4
	v_subrev_u32_e32 v4, 64, v4
	s_movk_i32 s16, 0x80
	v_cmp_gt_u32_e32 vcc, s16, v4
	s_mov_b64 s[54:55], vcc
	s_and_saveexec_b64 s[16:17], vcc
	s_cbranch_execz .Lswab_skip4
	v_max_u32_e32 v5, 16, v4
	v_ffbh_u32_e32 v6, v5
	v_lshlrev_b32_e32 v6, 1, v6
	v_sub_u32_e32 v7, 62, v6
	v_mul_lo_u32 v5, v5, v5
	v_lshlrev_b32_e64 v7, v7, 2
	v_cmp_ge_u32_e32 vcc, v5, v7
	s_nop 1
	v_cndmask_b32_e64 v5, 0, 1, vcc
	v_sub_u32_e32 v5, v5, v6
	v_add_u32_e32 v5, 0x46, v5
	v_cmp_gt_u32_e32 vcc, 16, v4
	s_nop 1
	v_cndmask_b32_e32 v4, v5, v4, vcc
	v_lshlrev_b32_e32 v4, 4, v4
	v_add3_u32 v4, v3, s26, v4
	v_ashrrev_i32_e32 v5, 31, v4
	v_lshl_add_u64 v[4:5], v[4:5], 2, s[6:7]
	global_load_dword v16, v[4:5], off
.Lswab_skip4:
	s_or_b64 exec, exec, s[16:17]
	s_waitcnt vmcnt(0)
	v_mul_f32_e32 v5, 0x3fb8aa3b, v12
	s_nop 0
	v_cndmask_b32_e64 v5, v8, v5, s[30:31]
	ds_write_b32 v0, v5
	v_mul_f32_e32 v5, 0x3fb8aa3b, v13
	s_nop 0
	v_cndmask_b32_e64 v5, v8, v5, s[40:41]
	ds_write_b32 v0, v5 offset:2048
	v_mul_f32_e32 v5, 0x3fb8aa3b, v14
	s_nop 0
	v_cndmask_b32_e64 v5, v8, v5, s[44:45]
	ds_write_b32 v0, v5 offset:4096
	v_mul_f32_e32 v5, 0x3fb8aa3b, v15
	s_nop 0
	v_cndmask_b32_e64 v5, v8, v5, s[48:49]
	ds_write_b32 v0, v5 offset:6144
	v_mul_f32_e32 v5, 0x3fb8aa3b, v16
	s_nop 0
	v_cndmask_b32_e64 v5, v8, v5, s[54:55]
	ds_write_b32 v0, v5 offset:8192

; #define LAS __attribute__((address_space(3)))
; __device__ __forceinline__ void moba_unit2(lbyte* lds, const bf16* QKV, bf16* AO, unsigned char* part, unsigned char* part3, const float* km2, const float* rel_bias, int b, int hm, int own) {
;     ...
;     for (int i = tid; i < 256 * 8; i += NT) { const int row = i >> 3, ch = i & 7; *(LAS u32x4*)(lds + MC_Q + row * KP64 + ch * 16) = *(const u32x4*)(Qh + ((size_t)own * 256 + row) * 64 + ch * 8); }
.LBB0_564:
	v_ashrrev_i32_e32 v12, 3, v2
	v_ashrrev_i32_e32 v13, 31, v12
	v_lshlrev_b64 v[8:9], 7, v[12:13]
	v_lshl_add_u64 v[64:65], v[6:7], 0, v[8:9]
	s_mov_b64 s[44:45], 0x2000
	v_lshl_add_u64 v[66:67], v[64:65], 0, s[44:45]
	v_lshl_add_u64 v[68:69], v[66:67], 0, s[44:45]
	v_lshl_add_u64 v[70:71], v[68:69], 0, s[44:45]
	global_load_dwordx4 v[46:49], v[64:65], off
	global_load_dwordx4 v[50:53], v[66:67], off
	global_load_dwordx4 v[54:57], v[68:69], off
	global_load_dwordx4 v[58:61], v[70:71], off
	v_mad_u64_u32 v[62:63], s[22:23], v12, s73, v[0:1]
	s_movk_i32 s13, 0x5ff

; #define LAS __attribute__((address_space(3)))
; __device__ __forceinline__ void moba_unit2(lbyte* lds, const bf16* QKV, bf16* AO, unsigned char* part, unsigned char* part3, const float* km2, const float* rel_bias, int b, int hm, int own) {
;     ...
;     for (int i = tid; i < 256 * 8; i += NT) { const int row = i >> 3, ch = i & 7; *(LAS u32x4*)(lds + MC_Q + row * KP64 + ch * 16) = *(const u32x4*)(Qh + ((size_t)own * 256 + row) * 64 + ch * 8); }
;     for (int idx = tid; idx < own * 64; idx += NT) { const int n = idx >> 6, d = idx & 63; const size_t blk = (size_t)b * 32 + n;
;         kmean[idx] = (km2[(blk * 2 + 0) * 512 + 64 * hm + d] + km2[(blk * 2 + 1) * 512 + 64 * hm + d]) * (1.0f / 256.0f); }
;     if (tid < 32) { tab[tid] = rel_bias[tid * 16 + 8 + hm] * LOG2E;
;         int tv = tid; if (tid >= 16) { const int eb = (tid - 8) >> 1; tv = ((tid - 8) & 1) ? (int)(1.41421356f * (float)(1 << eb)) + 1 : (1 << eb); } thr[tid] = tv; }
;     if (tid < 80) cnt[tid] = 0u;
;     __syncthreads();
;     for (int i = tid; i < MC_NDT; i += NT) dtab[i] = tab[t5_bucket(i)];
.LBB0_577:
	s_or_b64 exec, exec, s[8:9]
	s_movk_i32 s0, 0x50
	v_cmp_gt_i32_e32 vcc, s0, v2
	s_and_saveexec_b64 s[0:1], vcc
	v_add_u32_e32 v0, 0x21000, v0
	ds_write_b32 v0, v1
	s_or_b64 exec, exec, s[0:1]
	s_waitcnt vmcnt(0)
	ds_write_b128 v62, v[46:49]
	ds_write_b128 v62, v[50:53] offset:9216
	ds_write_b128 v62, v[54:57] offset:18432
	ds_write_b128 v62, v[58:61] offset:27648
	s_movk_i32 s0, 0xb54
	v_cmp_gt_i32_e32 vcc, s0, v2
	s_waitcnt vmcnt(0) lgkmcnt(0)
	s_barrier
	s_and_saveexec_b64 s[0:1], vcc
	s_cbranch_execz .LBB0_582
	v_lshl_add_u32 v0, v2, 2, s82
	s_mov_b64 s[8:9], 0
	v_mov_b32_e32 v3, v2

; __device__ __forceinline__ void moba_unit2(lbyte* lds, const bf16* QKV, bf16* AO, unsigned char* part, unsigned char* part3, const float* km2, const float* rel_bias, int b, int hm, int own) {
;     ...
;     if (tid == 0) { unsigned acc = 0u; for (int n = 0; n < own; ++n) { istart[n] = acc; const unsigned cn = (cnt[n] + 31u) >> 5; for (unsigned k = 0; k < cn; ++k) itemn[acc + k] = (unsigned char)n; acc += cn; } istart[own] = acc; }
.LBB0_631:
	s_or_b64 exec, exec, s[20:21]
	v_cmp_gt_u32_e32 vcc, 32, v2
	s_waitcnt lgkmcnt(0)
	s_barrier
	s_and_saveexec_b64 s[0:1], vcc
	s_cbranch_execz .LBB0_644
	v_lshlrev_b32_e32 v3, 2, v2
	v_add_u32_e32 v0, 0x21000, v3
	ds_read_b32 v0, v0
	v_add_u32_e32 v7, 0x21080, v3
	s_waitcnt lgkmcnt(0)
	v_add_u32_e32 v0, 31, v0
	v_lshrrev_b32_e32 v4, 5, v0
	v_mov_b32_e32 v5, v4
	s_nop 1
	v_add_u32_dpp v5, v5, v5 row_shr:1 row_mask:0xf bank_mask:0xf
	s_nop 1
	v_add_u32_dpp v5, v5, v5 row_shr:2 row_mask:0xf bank_mask:0xf
	s_nop 1
	v_add_u32_dpp v5, v5, v5 row_shr:4 row_mask:0xf bank_mask:0xf
	s_nop 1
	v_add_u32_dpp v5, v5, v5 row_shr:8 row_mask:0xf bank_mask:0xf
	s_nop 1
	v_add_u32_dpp v5, v5, v5 row_bcast:15 row_mask:0xa bank_mask:0xf
	s_nop 0
	v_sub_u32_e32 v6, v5, v4
	ds_write_b32 v7, v6
	v_add_u32_e32 v6, 0x1b000, v6
	v_cmp_lt_u32_e32 vcc, 0, v4
	s_and_b64 exec, exec, vcc
	ds_write_b8 v6, v2
	v_cmp_lt_u32_e32 vcc, 1, v4
	s_and_b64 exec, exec, vcc
	ds_write_b8 v6, v2 offset:1
	v_cmp_lt_u32_e32 vcc, 2, v4
	s_and_b64 exec, exec, vcc
	ds_write_b8 v6, v2 offset:2
	v_cmp_lt_u32_e32 vcc, 3, v4
	s_and_b64 exec, exec, vcc
	ds_write_b8 v6, v2 offset:3
	v_cmp_lt_u32_e32 vcc, 4, v4
	s_and_b64 exec, exec, vcc
	ds_write_b8 v6, v2 offset:4
	v_cmp_lt_u32_e32 vcc, 5, v4
	s_and_b64 exec, exec, vcc
	ds_write_b8 v6, v2 offset:5
	v_cmp_lt_u32_e32 vcc, 6, v4
	s_and_b64 exec, exec, vcc
	ds_write_b8 v6, v2 offset:6
	v_cmp_lt_u32_e32 vcc, 7, v4
	s_and_b64 exec, exec, vcc
	ds_write_b8 v6, v2 offset:7
